# m2 plus: hw0 waves skip the dead accumulator zeroing at the top of each scan chunk
# speedup vs baseline: 1.0064x; 1.0064x over previous
.LBB0_863:
	s_cmp_lg_u64 s[10:11], 0
	s_cbranch_scc1 .Lmy_scan_nz
	v_mov_b32_e32 v32, 0
	v_mov_b32_e32 v33, 0
	v_mov_b32_e32 v34, 0
	v_mov_b32_e32 v35, 0
	v_mov_b32_e32 v36, 0
	v_mov_b32_e32 v37, 0
	v_mov_b32_e32 v38, 0
	v_mov_b32_e32 v39, 0
	v_mov_b32_e32 v40, 0
	v_mov_b32_e32 v41, 0
	v_mov_b32_e32 v42, 0
	v_mov_b32_e32 v43, 0
	v_mov_b32_e32 v44, 0
	v_mov_b32_e32 v45, 0
	v_mov_b32_e32 v46, 0
	v_mov_b32_e32 v47, 0
	v_mov_b32_e32 v48, 0
	v_mov_b32_e32 v49, 0
	v_mov_b32_e32 v50, 0
	v_mov_b32_e32 v51, 0
	v_mov_b32_e32 v52, 0
	v_mov_b32_e32 v53, 0
	v_mov_b32_e32 v54, 0
	v_mov_b32_e32 v55, 0
	v_mov_b32_e32 v56, 0
	v_mov_b32_e32 v57, 0
	v_mov_b32_e32 v58, 0
	v_mov_b32_e32 v59, 0
	v_mov_b32_e32 v60, 0
	v_mov_b32_e32 v61, 0
	v_mov_b32_e32 v62, 0
	v_mov_b32_e32 v63, 0
.Lmy_scan_nz:
	s_and_saveexec_b64 s[50:51], s[10:11]
	s_cbranch_execz .LBB0_865
	v_lshlrev_b32_e32 v32, 16, v136
	v_and_b32_e32 v33, 0xffff0000, v136
	v_lshlrev_b32_e32 v34, 16, v137
	v_and_b32_e32 v35, 0xffff0000, v137
	v_lshlrev_b32_e32 v48, 16, v132
	v_and_b32_e32 v49, 0xffff0000, v132
	v_lshlrev_b32_e32 v50, 16, v133
	v_and_b32_e32 v51, 0xffff0000, v133
	v_lshlrev_b32_e32 v36, 16, v130
	v_and_b32_e32 v37, 0xffff0000, v130
	v_lshlrev_b32_e32 v38, 16, v131
	v_and_b32_e32 v39, 0xffff0000, v131
	v_lshlrev_b32_e32 v52, 16, v140
	v_and_b32_e32 v53, 0xffff0000, v140
	v_lshlrev_b32_e32 v54, 16, v141
	v_and_b32_e32 v55, 0xffff0000, v141
	v_lshlrev_b32_e32 v40, 16, v134
	v_and_b32_e32 v41, 0xffff0000, v134
	v_lshlrev_b32_e32 v42, 16, v135
	v_and_b32_e32 v43, 0xffff0000, v135
	v_lshlrev_b32_e32 v56, 16, v142
	v_and_b32_e32 v57, 0xffff0000, v142
	v_lshlrev_b32_e32 v58, 16, v143
	v_and_b32_e32 v59, 0xffff0000, v143
	v_lshlrev_b32_e32 v44, 16, v138
	v_and_b32_e32 v45, 0xffff0000, v138
	v_lshlrev_b32_e32 v46, 16, v139
	v_and_b32_e32 v47, 0xffff0000, v139
	v_lshlrev_b32_e32 v60, 16, v144
	v_and_b32_e32 v61, 0xffff0000, v144
	v_lshlrev_b32_e32 v62, 16, v145
	v_and_b32_e32 v63, 0xffff0000, v145

.LBB0_1130:
	s_ashr_i32 s13, s18, 5
	s_lshl_b32 s19, s13, 6
	s_lshl_b32 s13, s13, 8
	s_and_b32 s12, s16, 0xc0
	s_and_b32 s20, s19, 0xffffff00
	s_and_b32 s19, s13, 0x300
	s_lshl_b32 s13, s14, 11
	v_or_b32_e32 v0, s19, v17
	s_and_b32 s13, s13, 0x70000
	s_or_b32 s12, s12, s20
	v_lshl_or_b32 v4, v0, 11, s13
	v_add_u32_e32 v0, s12, v18
	v_ashrrev_i32_e32 v1, 31, v0
	v_lshlrev_b64 v[0:1], 11, v[0:1]
	v_lshl_add_u64 v[10:11], v[6:7], 0, v[4:5]
	v_lshl_add_u64 v[12:13], v[8:9], 0, v[0:1]
	v_mov_b32_e32 v176, v10
	v_mov_b32_e32 v177, v11
	v_mov_b32_e32 v178, v12
	v_mov_b32_e32 v179, v13
	s_lshl_b32 s12, s18, 3
	s_and_b32 s12, s12, 0xc0
	s_add_i32 s20, s20, s12
	v_add_u32_e32 v4, s20, v15
	v_or_b32_e32 v10, v4, v14
	s_lshl_b32 s12, s18, 5
	v_ashrrev_i32_e32 v11, 31, v10
	s_and_b32 s12, s12, 0xe0
	v_lshlrev_b64 v[20:21], 12, v[10:11]
	s_or_b32 s12, s19, s12
	v_lshl_add_u64 v[12:13], s[6:7], 0, v[20:21]
	v_or_b32_e32 v19, s12, v16
	v_lshl_add_u64 v[10:11], s[4:5], 0, v[20:21]
	v_lshl_add_u64 v[12:13], v[12:13], 0, s[10:11]
	v_cmp_gt_u32_e32 vcc, s3, v4
	v_lshlrev_b32_e32 v4, 2, v19
	s_nop 1
	v_cndmask_b32_e32 v11, v13, v11, vcc
	v_cndmask_b32_e32 v10, v12, v10, vcc
	v_lshl_add_u64 v[10:11], v[10:11], 0, v[4:5]
	global_load_dwordx4 v[10:13], v[10:11], off
	v_lshl_add_u64 v[20:21], s[8:9], 0, v[20:21]
	v_lshl_add_u64 v[20:21], v[20:21], 0, v[4:5]
	v_readfirstlane_b32 s88, v170
	s_nop 3
	s_lshr_b32 s88, s88, 6
	s_and_b32 s89, s88, 1
	s_lshr_b32 s90, s88, 1
	s_lshl_b32 s91, s88, 8
	s_lshl_b32 s96, s89, 15
	s_sub_u32 s92, s91, s96
	s_subb_u32 s93, 0, 0
	s_mul_i32 s96, s90, 32768
	s_add_u32 s97, s91, 0
	s_sub_u32 s94, s97, s96
	s_subb_u32 s95, 0, 0
	v_lshl_add_u64 v[172:173], v[176:177], 0, s[92:93]
	v_lshl_add_u64 v[84:85], v[178:179], 0, s[94:95]
	s_mov_b64 s[96:97], 0x8000
	v_lshl_add_u64 v[174:175], v[172:173], 0, s[96:97]
	s_mov_b64 s[96:97], 32768
	v_lshl_add_u64 v[86:87], v[84:85], 0, s[96:97]
	v_lshl_add_u64 v[88:89], v[86:87], 0, s[96:97]
	v_lshl_add_u64 v[90:91], v[88:89], 0, s[96:97]
	global_load_dwordx4 v[24:27], v[84:85], off offset:0
	global_load_dwordx4 v[28:31], v[86:87], off offset:0
	global_load_dwordx4 v[32:35], v[88:89], off offset:0
	global_load_dwordx4 v[36:39], v[90:91], off offset:0
	global_load_dwordx4 v[40:43], v[172:173], off offset:0
	global_load_dwordx4 v[44:47], v[174:175], off offset:0
	global_load_dwordx4 v[48:51], v[84:85], off offset:64
	global_load_dwordx4 v[52:55], v[86:87], off offset:64
	global_load_dwordx4 v[56:59], v[88:89], off offset:64
	global_load_dwordx4 v[60:63], v[90:91], off offset:64
	global_load_dwordx4 v[64:67], v[172:173], off offset:64
	global_load_dwordx4 v[68:71], v[174:175], off offset:64
	global_load_dwordx4 v[72:75], v[84:85], off offset:128
	global_load_dwordx4 v[76:79], v[86:87], off offset:128
	global_load_dwordx4 v[80:83], v[88:89], off offset:128
	global_load_dwordx4 v[92:95], v[90:91], off offset:128
	global_load_dwordx4 v[96:99], v[172:173], off offset:128
	global_load_dwordx4 v[100:103], v[174:175], off offset:128
	global_load_dwordx4 v[104:107], v[84:85], off offset:192
	global_load_dwordx4 v[108:111], v[86:87], off offset:192
	global_load_dwordx4 v[112:115], v[88:89], off offset:192
	global_load_dwordx4 v[116:119], v[90:91], off offset:192
	global_load_dwordx4 v[120:123], v[172:173], off offset:192
	global_load_dwordx4 v[124:127], v[174:175], off offset:192
	v_mov_b32_e32 v128, 0
	v_mov_b32_e32 v129, 0
	v_mov_b32_e32 v130, 0
	v_mov_b32_e32 v131, 0
	v_mov_b32_e32 v132, 0
	v_mov_b32_e32 v133, 0
	v_mov_b32_e32 v134, 0
	v_mov_b32_e32 v135, 0
	v_mov_b32_e32 v136, 0
	v_mov_b32_e32 v137, 0
	v_mov_b32_e32 v138, 0
	v_mov_b32_e32 v139, 0
	v_mov_b32_e32 v140, 0
	v_mov_b32_e32 v141, 0
	v_mov_b32_e32 v142, 0
	v_mov_b32_e32 v143, 0
	v_mov_b32_e32 v144, 0
	v_mov_b32_e32 v145, 0
	v_mov_b32_e32 v146, 0
	v_mov_b32_e32 v147, 0
	v_mov_b32_e32 v148, 0
	v_mov_b32_e32 v149, 0
	v_mov_b32_e32 v150, 0
	v_mov_b32_e32 v151, 0
	v_mov_b32_e32 v152, 0
	v_mov_b32_e32 v153, 0
	v_mov_b32_e32 v154, 0
	v_mov_b32_e32 v155, 0
	v_mov_b32_e32 v156, 0
	v_mov_b32_e32 v157, 0
	v_mov_b32_e32 v158, 0
	v_mov_b32_e32 v159, 0
	v_and_b32_e32 v160, 63, v170
	v_lshlrev_b32_e32 v160, 4, v160
	s_lshl_b32 s96, s88, 10
	v_add_u32_e32 v161, s96, v160
	s_lshl_b32 s96, s88, 13
	v_add_u32_e32 v162, s96, v160
	s_waitcnt vmcnt(18)
	v_mfma_f32_16x16x32_bf16 v[128:131], v[40:43], v[24:27], v[128:131]
	v_mfma_f32_16x16x32_bf16 v[132:135], v[44:47], v[24:27], v[132:135]
	v_mfma_f32_16x16x32_bf16 v[136:139], v[40:43], v[28:31], v[136:139]
	v_mfma_f32_16x16x32_bf16 v[140:143], v[44:47], v[28:31], v[140:143]
	v_mfma_f32_16x16x32_bf16 v[144:147], v[40:43], v[32:35], v[144:147]
	v_mfma_f32_16x16x32_bf16 v[148:151], v[44:47], v[32:35], v[148:151]
	v_mfma_f32_16x16x32_bf16 v[152:155], v[40:43], v[36:39], v[152:155]
	v_mfma_f32_16x16x32_bf16 v[156:159], v[44:47], v[36:39], v[156:159]
	s_waitcnt vmcnt(12)
	v_mfma_f32_16x16x32_bf16 v[128:131], v[64:67], v[48:51], v[128:131]
	v_mfma_f32_16x16x32_bf16 v[132:135], v[68:71], v[48:51], v[132:135]
	v_mfma_f32_16x16x32_bf16 v[136:139], v[64:67], v[52:55], v[136:139]
	v_mfma_f32_16x16x32_bf16 v[140:143], v[68:71], v[52:55], v[140:143]
	v_mfma_f32_16x16x32_bf16 v[144:147], v[64:67], v[56:59], v[144:147]
	v_mfma_f32_16x16x32_bf16 v[148:151], v[68:71], v[56:59], v[148:151]
	v_mfma_f32_16x16x32_bf16 v[152:155], v[64:67], v[60:63], v[152:155]
	v_mfma_f32_16x16x32_bf16 v[156:159], v[68:71], v[60:63], v[156:159]
	s_waitcnt vmcnt(6)
	v_mfma_f32_16x16x32_bf16 v[128:131], v[96:99], v[72:75], v[128:131]
	v_mfma_f32_16x16x32_bf16 v[132:135], v[100:103], v[72:75], v[132:135]
	v_mfma_f32_16x16x32_bf16 v[136:139], v[96:99], v[76:79], v[136:139]
	v_mfma_f32_16x16x32_bf16 v[140:143], v[100:103], v[76:79], v[140:143]
	v_mfma_f32_16x16x32_bf16 v[144:147], v[96:99], v[80:83], v[144:147]
	v_mfma_f32_16x16x32_bf16 v[148:151], v[100:103], v[80:83], v[148:151]
	v_mfma_f32_16x16x32_bf16 v[152:155], v[96:99], v[92:95], v[152:155]
	v_mfma_f32_16x16x32_bf16 v[156:159], v[100:103], v[92:95], v[156:159]
	s_waitcnt vmcnt(0)
	v_mfma_f32_16x16x32_bf16 v[128:131], v[120:123], v[104:107], v[128:131]
	v_mfma_f32_16x16x32_bf16 v[132:135], v[124:127], v[104:107], v[132:135]
	v_mfma_f32_16x16x32_bf16 v[136:139], v[120:123], v[108:111], v[136:139]
	v_mfma_f32_16x16x32_bf16 v[140:143], v[124:127], v[108:111], v[140:143]
	v_mfma_f32_16x16x32_bf16 v[144:147], v[120:123], v[112:115], v[144:147]
	v_mfma_f32_16x16x32_bf16 v[148:151], v[124:127], v[112:115], v[148:151]
	v_mfma_f32_16x16x32_bf16 v[152:155], v[120:123], v[116:119], v[152:155]
	v_mfma_f32_16x16x32_bf16 v[156:159], v[124:127], v[116:119], v[156:159]
	s_nop 8
	ds_write_b128 v161, v[128:131] offset:0
	ds_write_b128 v161, v[132:135] offset:8192
	ds_write_b128 v161, v[136:139] offset:16384
	ds_write_b128 v161, v[140:143] offset:24576
	ds_write_b128 v161, v[144:147] offset:32768
	ds_write_b128 v161, v[148:151] offset:40960
	ds_write_b128 v161, v[152:155] offset:49152
	ds_write_b128 v161, v[156:159] offset:57344
	s_waitcnt lgkmcnt(0)
	s_barrier
	ds_read_b128 v[24:27], v162 offset:0
	ds_read_b128 v[28:31], v162 offset:1024
	ds_read_b128 v[32:35], v162 offset:2048
	ds_read_b128 v[36:39], v162 offset:3072
	ds_read_b128 v[40:43], v162 offset:4096
	ds_read_b128 v[44:47], v162 offset:5120
	ds_read_b128 v[48:51], v162 offset:6144
	ds_read_b128 v[52:55], v162 offset:7168
	s_waitcnt lgkmcnt(0)
	v_pk_add_f32 v[0:1], v[24:25], v[28:29]
	v_pk_add_f32 v[2:3], v[26:27], v[30:31]
	v_pk_add_f32 v[0:1], v[0:1], v[32:33]
	v_pk_add_f32 v[2:3], v[2:3], v[34:35]
	v_pk_add_f32 v[0:1], v[0:1], v[36:37]
	v_pk_add_f32 v[2:3], v[2:3], v[38:39]
	v_pk_add_f32 v[0:1], v[0:1], v[40:41]
	v_pk_add_f32 v[2:3], v[2:3], v[42:43]
	v_pk_add_f32 v[0:1], v[0:1], v[44:45]
	v_pk_add_f32 v[2:3], v[2:3], v[46:47]
	v_pk_add_f32 v[0:1], v[0:1], v[48:49]
	v_pk_add_f32 v[2:3], v[2:3], v[50:51]
	v_pk_add_f32 v[0:1], v[0:1], v[52:53]
	v_pk_add_f32 v[2:3], v[2:3], v[54:55]
	s_add_i32 s18, s18, s30
	s_add_i32 s14, s14, s15
	s_add_i32 s16, s16, s17
	s_cmpk_gt_i32 s18, 0xff
	s_waitcnt vmcnt(0)
	v_pk_add_f32 v[2:3], v[2:3], v[12:13]
	v_pk_add_f32 v[0:1], v[0:1], v[10:11]
	global_store_dwordx4 v[20:21], v[0:3], off
	s_cbranch_scc0 .LBB0_1130
